# attention early-exit threshold 2^-150 -> 2^-134 (every remaining weight already rounds to bf16 zero: bit-identical output), on top of v9
# baseline (speedup 1.0000x reference)
; template <bool PR>
; __device__ __forceinline__ void attn_unit(const Args& a, const bf16_t* QB, bf16_t* AO, const bf16_t* KBp, const bf16_t* VTp, int qt, int h, int lane) {
;     const int r32 = lane & 31, hi = lane >> 5;
;     const float *Kd, *Vd, *Kc, *Vc; int nprev; size_t qrow0;
;     if (qt < 1024) { const int b = qt >> 7, tq = qt & 127; qrow0 = (size_t)qt * 32;
;         Kc = a.out + OFF_KP + (size_t)b * 4096 * 512 + h * 64; Vc = a.out + OFF_VP + (size_t)b * 4096 * 512 + h * 64;
;         Kd = Kc + (size_t)tq * 32 * 512; Vd = Vc + (size_t)tq * 32 * 512; nprev = tq; }
;     else { const int bs = qt - 1024; qrow0 = (size_t)MP + (size_t)bs * 32;
;         Kd = a.out + OFF_KS + (size_t)bs * 32 * 512 + h * 64; Vd = a.out + OFF_VS + (size_t)bs * 32 * 512 + h * 64;
;         Kc = a.in[I_CK] + (size_t)bs * 4096 * 512 + h * 64; Vc = a.in[I_CV] + (size_t)bs * 4096 * 512 + h * 64; nprev = 128; }
;     bf16x8 qf[4];
;     { const bf16_t* Qp = QB + (qrow0 + r32) * 512 + h * 64 + hi * 8;
; #pragma unroll
;       for (int kk = 0; kk < 4; ++kk) qf[kk] = __builtin_nontemporal_load((const bf16x8*)(Qp + kk * 16)); }
;     f32x16 o0, o1;
; #pragma unroll
;     for (int r = 0; r < 16; ++r) { o0[r] = 0.f; o1[r] = 0.f; }
;     float Cm = 1.f; int Ce = 0;
;     constexpr int DP = PR ? 3 : 1;
;     f32x4 kr[8]; float vr[32];
;     bf16x8 krb[DP][4]; u32x2 vrb[DP][8];
;     const bf16_t* Kbb = KBp + (size_t)(((qt >> 7) * 8 + h) * 128) * 2048 + r32 * 16 + hi * 8;
;     const bf16_t* Vtb = VTp + ((size_t)(((qt >> 7) * 8 + h) * 1024 + hi) * 64 + r32) * 4;
;     ...
;         for (int r = 0; r < 16; ++r) { const float z2 = s[r]; const float e = __builtin_amdgcn_exp2f(-fabsf(z2)); const float rc = __builtin_amdgcn_rcpf(1.f + e); const float t = e * rc;
;             const bool pos = z2 >= 0.f; const bool valid = (it != 0) || (crow(r, hi) < r32);
;             sg[r] = valid ? (pos ? rc : t) : 0.f; om[r] = valid ? (pos ? t : rc) : 1.f; }
;         const float G0 = (om[0] * om[1]) * (om[2] * om[3]), G1 = (om[4] * om[5]) * (om[6] * om[7]), G2 = (om[8] * om[9]) * (om[10] * om[11]), G3 = (om[12] * om[13]) * (om[14] * om[15]);
;         const float P0 = __shfl_xor(G0, 32), P1 = __shfl_xor(G1, 32), P2 = __shfl_xor(G2, 32), P3 = __shfl_xor(G3, 32);
;         const float t3 = G3 * P3, t2 = G2 * P2, t1 = G1 * P1, t0 = G0 * P0;
;         const float Cs = ldexpf(Cm, Ce);
;         float base[4];
.LBB0_593:
	v_readlane_b32 s0, v241, 23
	s_cmpk_gt_u32 s0, 0x20ff
	v_cmp_eq_u32_e64 s[54:55], 0, v180
	v_readlane_b32 s56, v241, 28
	v_readlane_b32 s1, v241, 24
	v_readlane_b32 s57, v241, 29
	v_writelane_b32 v241, s94, 43
	s_cbranch_scc1 .LBB0_645
	v_and_b32_e32 v182, 31, v181
	v_lshrrev_b32_e32 v5, 5, v180
	v_mov_b32_e32 v185, 0
	v_lshlrev_b32_e32 v184, 5, v182
	v_lshl_add_u64 v[0:1], s[16:17], 0, v[184:185]
	v_lshlrev_b32_e32 v2, 4, v5
	v_mov_b32_e32 v3, v185
	v_lshl_add_u64 v[188:189], v[0:1], 0, v[2:3]
	v_lshlrev_b32_e32 v0, 2, v5
	v_or_b32_e32 v1, 1, v0
	v_cmp_lt_u32_e64 s[8:9], v1, v182
	v_or_b32_e32 v1, 2, v0
	v_cmp_lt_u32_e64 s[10:11], v1, v182
	v_or_b32_e32 v1, 3, v0
	v_cmp_lt_u32_e64 s[12:13], v1, v182
	v_or_b32_e32 v1, 8, v0
	v_cmp_lt_u32_e64 s[14:15], v1, v182
	v_or_b32_e32 v1, 9, v0
	s_add_u32 s0, s90, 0x383800
	v_cmp_lt_u32_e64 s[16:17], v1, v182
	v_or_b32_e32 v1, 10, v0
	s_addc_u32 s1, s91, 0
	v_cmp_lt_u32_e64 s[18:19], v1, v182
	v_or_b32_e32 v1, 11, v0
	v_writelane_b32 v241, s70, 44
	s_add_u32 s57, s90, 0x1dd00000
	v_cmp_lt_u32_e64 s[20:21], v1, v182
	v_or_b32_e32 v1, 16, v0
	v_writelane_b32 v241, s0, 45
	s_addc_u32 s60, s91, 0
	v_cmp_lt_u32_e64 s[22:23], v1, v182
	v_or_b32_e32 v1, 17, v0
	v_writelane_b32 v241, s1, 46
	v_cmp_lt_u32_e64 s[24:25], v1, v182
	v_or_b32_e32 v1, 18, v0
	s_add_u32 s0, s88, 0x10688000
	v_cmp_lt_u32_e64 s[26:27], v1, v182
	v_or_b32_e32 v1, 19, v0
	v_writelane_b32 v241, s0, 47
	s_addc_u32 s0, s89, 0
	v_cmp_lt_u32_e64 s[28:29], v1, v182
	v_or_b32_e32 v1, 24, v0
	v_writelane_b32 v241, s0, 48
	s_add_u32 s0, s88, 0x10488000
	v_cmp_lt_u32_e64 s[30:31], v1, v182
	v_or_b32_e32 v1, 25, v0
	v_writelane_b32 v241, s0, 49
	s_addc_u32 s0, s89, 0
	v_cmp_lt_u32_e64 s[34:35], v1, v182
	v_or_b32_e32 v1, 26, v0
	v_writelane_b32 v241, s0, 50
	v_cmp_lt_u32_e64 s[36:37], v1, v182
	v_and_b32_e32 v1, 32, v181
	v_readlane_b32 s0, v241, 23
	v_cmp_lt_u32_e64 s[6:7], v0, v182
	v_or_b32_e32 v0, 27, v0
	v_lshrrev_b32_e32 v1, 1, v1
	v_readlane_b32 s1, v241, 24
	v_writelane_b32 v241, s54, 51
	v_lshlrev_b32_e32 v186, 3, v5
	v_cmp_lt_u32_e64 s[38:39], v0, v182
	v_lshlrev_b32_e32 v0, 12, v5
	v_lshlrev_b32_e32 v2, 9, v182
	v_lshlrev_b32_e32 v4, 11, v5
	v_or_b32_e32 v184, v184, v1
	s_movk_i32 s2, 0xd000
	v_writelane_b32 v241, s55, 52
	s_mov_b32 s93, 0
	v_mov_b32_e32 v177, v185
	v_cmp_gt_u32_e64 s[4:5], 32, v180
	v_lshl_or_b32 v183, v5, 6, v182
	v_lshl_add_u64 v[190:191], s[90:91], 0, v[184:185]
	s_movk_i32 s64, 0xff7a
	s_mov_b32 s3, -1
	s_movk_i32 s70, 0x1000
	s_movk_i32 s71, 0x4000
	s_movk_i32 s66, 0x5000
	s_mov_b32 s65, 0x8000
	s_mov_b32 s67, 0x9000
	s_mov_b32 s62, 0xc000
	v_lshlrev_b32_e32 v192, 2, v2
	v_lshlrev_b32_e32 v194, 2, v4
	v_lshlrev_b32_e32 v196, 1, v0
	v_lshlrev_b32_e32 v184, 1, v186
	v_mbcnt_hi_u32_b32 v187, -1, v179
	s_mov_b32 s63, s0
	v_writelane_b32 v241, s57, 53
	v_writelane_b32 v241, s60, 54
	s_branch .LBB0_597
